# fix DSA epilogue wait count after Y-store widening (vmcnt 4 to 2), otherwise same as P13-pipelined version
# baseline (speedup 1.0000x reference)
; #define GAS __attribute__((address_space(1)))
; __device__ __forceinline__ unsigned pk2(float lo, float hi) { f32x2_t v = {lo, hi}; bf16x2_t b = __builtin_convertvector(v, bf16x2_t); return __builtin_bit_cast(unsigned, b); }
; __device__ __forceinline__ f32x16 mfma32(bf16x8 a, bf16x8 b, f32x16 c) { return __builtin_amdgcn_mfma_f32_32x32x16_bf16(a, b, c, 0, 0, 0); }
; __device__ __forceinline__ void dsa_unit32(const Args& a, LAS unsigned char* lds, const LAS unsigned long long* maskl, int b, int qb, int tid, int wave, int lane) {
;     ...
;     l += __shfl_xor(l, 32);
;     const float il = 1.f / l;
;     bf16x8 of[8];
; #pragma unroll
;     for (int ks = 0; ks < 8; ++ks) { const int ct = ks >> 1, o8 = 8 * (ks & 1); u32x4 w;
;         w.x = pk2(O[ct][o8 + 0] * il, O[ct][o8 + 1] * il); w.y = pk2(O[ct][o8 + 2] * il, O[ct][o8 + 3] * il);
;         w.z = pk2(O[ct][o8 + 4] * il, O[ct][o8 + 5] * il); w.w = pk2(O[ct][o8 + 6] * il, O[ct][o8 + 7] * il); of[ks] = __builtin_bit_cast(bf16x8, w); }
; #pragma unroll
;     for (int vt = 0; vt < 2; ++vt) {
;         f32x16 acc;
; #pragma unroll
;         for (int i = 0; i < 16; ++i) acc[i] = 0.f;
;         const GAS bf16* wr = wuv + (size_t)(h * 64 + 32 * vt + l31) * 128 + 4 * hi;
; #pragma unroll
;         for (int ks = 0; ks < 8; ++ks) acc = mfma32(cat8(*(const GAS u32x2*)(wr + 16 * ks), *(const GAS u32x2*)(wr + 16 * ks + 8)), of[ks], acc);
.LBB0_1073:
	v_readlane_b32 s0, v254, 32
	v_readlane_b32 s1, v254, 33
	v_lshlrev_b32_e32 v92, 1, v182
	v_or_b32_e32 v90, s0, v5
	v_readlane_b32 s0, v254, 30
	v_mov_b32_e32 v93, v4
	v_readlane_b32 s1, v254, 31
	v_ashrrev_i32_e32 v91, 31, v90
	v_lshlrev_b64 v[0:1], 8, v[90:91]
	v_lshl_add_u64 v[98:99], s[0:1], 0, v[92:93]
	v_lshl_add_u64 v[96:97], v[98:99], 0, v[0:1]
	v_readlane_b32 s0, v254, 34
	v_lshlrev_b64 v[94:95], 11, v[178:179]
	v_readlane_b32 s1, v254, 35
	v_or_b32_e32 v100, 32, v90
	ds_bpermute_b32 v5, v181, v194
	v_lshl_add_u64 v[94:95], s[0:1], 0, v[94:95]
	v_lshl_add_u64 v[102:103], v[94:95], 0, v[92:93]
	v_lshl_add_u64 v[124:125], v[102:103], 0, v[92:93]
	v_lshl_add_u64 v[120:121], v[96:97], 0, v[92:93]
	global_load_dwordx4 v[0:3], v[120:121], off
	global_load_dwordx4 v[70:73], v[120:121], off offset:32
	global_load_dwordx4 v[74:77], v[120:121], off offset:64
	global_load_dwordx4 v[78:81], v[120:121], off offset:96
	global_load_dwordx4 v[82:85], v[120:121], off offset:128
	global_load_dwordx4 v[86:89], v[120:121], off offset:160
	global_load_dwordx4 v[90:93], v[120:121], off offset:192
	global_load_dwordx4 v[94:97], v[120:121], off offset:224
	s_nop 0
	s_waitcnt lgkmcnt(0)
	v_add_f32_e32 v5, v194, v5
	v_div_scale_f32 v104, s[0:1], v5, v5, 1.0
	v_rcp_f32_e32 v105, v104
	v_ashrrev_i32_e32 v101, 31, v100
	v_lshlrev_b64 v[100:101], 8, v[100:101]
	v_lshl_add_u64 v[98:99], v[98:99], 0, v[100:101]
	v_lshlrev_b32_e32 v122, 1, v182
	v_mov_b32_e32 v123, v4
	v_lshl_add_u64 v[122:123], v[98:99], 0, v[122:123]
	global_load_dwordx4 v[146:149], v[122:123], off
	global_load_dwordx4 v[150:153], v[122:123], off offset:32
	global_load_dwordx4 v[154:157], v[122:123], off offset:64
	global_load_dwordx4 v[158:161], v[122:123], off offset:96
	global_load_dwordx4 v[162:165], v[122:123], off offset:128
	global_load_dwordx4 v[166:169], v[122:123], off offset:160
	global_load_dwordx4 v[170:173], v[122:123], off offset:192
	global_load_dwordx4 v[174:177], v[122:123], off offset:224
	v_fma_f32 v101, -v104, v105, 1.0
	v_div_scale_f32 v100, vcc, 1.0, v5, 1.0
	v_fmac_f32_e32 v105, v101, v105
	v_mul_f32_e32 v101, v100, v105
	v_fma_f32 v106, -v104, v101, v100
	v_fmac_f32_e32 v101, v106, v105
	v_fma_f32 v100, -v104, v101, v100
	v_div_fmas_f32 v100, v100, v105, v101
	v_div_fixup_f32 v100, v100, v5, 1.0
	v_pk_mul_f32 v[54:55], v[54:55], v[100:101] op_sel_hi:[1,0]
	v_pk_mul_f32 v[56:57], v[56:57], v[100:101] op_sel_hi:[1,0]
	v_pk_mul_f32 v[58:59], v[58:59], v[100:101] op_sel_hi:[1,0]
	v_pk_mul_f32 v[60:61], v[60:61], v[100:101] op_sel_hi:[1,0]
	v_pk_mul_f32 v[112:113], v[38:39], v[100:101] op_sel_hi:[1,0]
	v_pk_mul_f32 v[114:115], v[40:41], v[100:101] op_sel_hi:[1,0]
	v_cvt_pk_bf16_f32 v38, v54, v55
	v_cvt_pk_bf16_f32 v39, v56, v57
	v_cvt_pk_bf16_f32 v40, v58, v59
	v_cvt_pk_bf16_f32 v41, v60, v61
	v_pk_mul_f32 v[104:105], v[62:63], v[100:101] op_sel_hi:[1,0]
	v_pk_mul_f32 v[106:107], v[64:65], v[100:101] op_sel_hi:[1,0]
	v_pk_mul_f32 v[108:109], v[66:67], v[100:101] op_sel_hi:[1,0]
	v_pk_mul_f32 v[110:111], v[68:69], v[100:101] op_sel_hi:[1,0]
	v_pk_mul_f32 v[116:117], v[42:43], v[100:101] op_sel_hi:[1,0]
	v_pk_mul_f32 v[118:119], v[44:45], v[100:101] op_sel_hi:[1,0]
	v_cvt_pk_bf16_f32 v42, v112, v113
	v_cvt_pk_bf16_f32 v43, v114, v115
	v_cvt_pk_bf16_f32 v44, v116, v117
	v_cvt_pk_bf16_f32 v45, v118, v119
	v_pk_mul_f32 v[46:47], v[46:47], v[100:101] op_sel_hi:[1,0]
	v_pk_mul_f32 v[48:49], v[48:49], v[100:101] op_sel_hi:[1,0]
	v_pk_mul_f32 v[50:51], v[50:51], v[100:101] op_sel_hi:[1,0]
	v_pk_mul_f32 v[52:53], v[52:53], v[100:101] op_sel_hi:[1,0]
	v_pk_mul_f32 v[30:31], v[30:31], v[100:101] op_sel_hi:[1,0]
	v_pk_mul_f32 v[32:33], v[32:33], v[100:101] op_sel_hi:[1,0]
	v_pk_mul_f32 v[34:35], v[34:35], v[100:101] op_sel_hi:[1,0]
	v_pk_mul_f32 v[36:37], v[36:37], v[100:101] op_sel_hi:[1,0]
	v_cvt_pk_bf16_f32 v30, v30, v31
	v_cvt_pk_bf16_f32 v31, v32, v33
	v_cvt_pk_bf16_f32 v32, v34, v35
	v_cvt_pk_bf16_f32 v33, v36, v37
	v_pk_mul_f32 v[6:7], v[6:7], v[100:101] op_sel_hi:[1,0]
	v_pk_mul_f32 v[8:9], v[8:9], v[100:101] op_sel_hi:[1,0]
	v_pk_mul_f32 v[10:11], v[10:11], v[100:101] op_sel_hi:[1,0]
	v_pk_mul_f32 v[12:13], v[12:13], v[100:101] op_sel_hi:[1,0]
	v_cvt_pk_bf16_f32 v34, v6, v7
	v_cvt_pk_bf16_f32 v35, v8, v9
	s_waitcnt vmcnt(8)
; #define GAS __attribute__((address_space(1)))
; __device__ __forceinline__ unsigned pk2(float lo, float hi) { f32x2_t v = {lo, hi}; bf16x2_t b = __builtin_convertvector(v, bf16x2_t); return __builtin_bit_cast(unsigned, b); }
; __device__ __forceinline__ f32x16 mfma32(bf16x8 a, bf16x8 b, f32x16 c) { return __builtin_amdgcn_mfma_f32_32x32x16_bf16(a, b, c, 0, 0, 0); }
; __device__ __forceinline__ void dsa_unit32(const Args& a, LAS unsigned char* lds, const LAS unsigned long long* maskl, int b, int qb, int tid, int wave, int lane) {
;     ...
;     for (int vt = 0; vt < 2; ++vt) {
;         f32x16 acc;
; #pragma unroll
;         for (int i = 0; i < 16; ++i) acc[i] = 0.f;
;         const GAS bf16* wr = wuv + (size_t)(h * 64 + 32 * vt + l31) * 128 + 4 * hi;
; #pragma unroll
;         for (int ks = 0; ks < 8; ++ks) acc = mfma32(cat8(*(const GAS u32x2*)(wr + 16 * ks), *(const GAS u32x2*)(wr + 16 * ks + 8)), of[ks], acc);
; #pragma unroll
;         for (int g = 0; g < 4; ++g) { u32x2 w; w.x = pk2(acc[4 * g], acc[4 * g + 1]); w.y = pk2(acc[4 * g + 2], acc[4 * g + 3]);
;             *(GAS u32x2*)(Y + (rowb + t0 + l31) * DM + 512 + h * 64 + 32 * vt + 8 * g + 4 * hi) = w; }
;     }
	v_permlane32_swap_b32_e32 v0, v2
	v_permlane32_swap_b32_e32 v1, v3
	v_permlane32_swap_b32_e32 v70, v72
	v_permlane32_swap_b32_e32 v71, v73
	v_permlane32_swap_b32_e32 v74, v76
	v_permlane32_swap_b32_e32 v75, v77
	v_permlane32_swap_b32_e32 v78, v80
	v_permlane32_swap_b32_e32 v79, v81
	v_permlane32_swap_b32_e32 v82, v84
	v_permlane32_swap_b32_e32 v83, v85
	v_permlane32_swap_b32_e32 v86, v88
	v_permlane32_swap_b32_e32 v87, v89
	v_permlane32_swap_b32_e32 v90, v92
	v_permlane32_swap_b32_e32 v91, v93
	v_permlane32_swap_b32_e32 v94, v96
	v_permlane32_swap_b32_e32 v95, v97
	s_nop 1
	v_mfma_f32_32x32x16_bf16 v[54:69], v[0:3], v[38:41], 0
	v_cvt_pk_bf16_f32 v0, v104, v105
	v_cvt_pk_bf16_f32 v1, v106, v107
	v_cvt_pk_bf16_f32 v2, v108, v109
	v_cvt_pk_bf16_f32 v3, v110, v111
	v_cvt_pk_bf16_f32 v36, v10, v11
	v_cvt_pk_bf16_f32 v37, v12, v13
	v_pk_mul_f32 v[14:15], v[14:15], v[100:101] op_sel_hi:[1,0]
	v_mfma_f32_32x32x16_bf16 v[54:69], v[70:73], v[0:3], v[54:69]
	v_mul_f32_e64 v70, v22, v100
	v_mul_f32_e64 v71, v23, v100
	v_mul_f32_e64 v72, v24, v100
	v_mul_f32_e64 v73, v25, v100
	v_cvt_pk_bf16_f32 v22, v46, v47
	v_cvt_pk_bf16_f32 v23, v48, v49
	v_cvt_pk_bf16_f32 v24, v50, v51
	v_cvt_pk_bf16_f32 v25, v52, v53
	v_pk_mul_f32 v[6:7], v[16:17], v[100:101] op_sel_hi:[1,0]
	v_mfma_f32_32x32x16_bf16 v[54:69], v[74:77], v[42:45], v[54:69]
	v_mul_f32_e64 v74, v26, v100
	v_mul_f32_e64 v75, v27, v100
	v_mul_f32_e64 v76, v28, v100
	v_mul_f32_e64 v77, v29, v100
	v_cvt_pk_bf16_f32 v26, v70, v71
	v_cvt_pk_bf16_f32 v27, v72, v73
	v_cvt_pk_bf16_f32 v28, v74, v75
	v_cvt_pk_bf16_f32 v29, v76, v77
	v_pk_mul_f32 v[8:9], v[18:19], v[100:101] op_sel_hi:[1,0]
	v_mfma_f32_32x32x16_bf16 v[54:69], v[78:81], v[22:25], v[54:69]
	v_mul_f32_e64 v10, v20, v100
	v_mul_f32_e64 v11, v21, v100
	v_cvt_pk_bf16_f32 v46, v14, v15
	v_cvt_pk_bf16_f32 v47, v6, v7
	v_cvt_pk_bf16_f32 v48, v8, v9
	v_cvt_pk_bf16_f32 v49, v10, v11
	s_mov_b64 s[0:1], 0
	v_mfma_f32_32x32x16_bf16 v[54:69], v[82:85], v[26:29], v[54:69]
	v_mfma_f32_32x32x16_bf16 v[54:69], v[86:89], v[30:33], v[54:69]
	v_mfma_f32_32x32x16_bf16 v[54:69], v[90:93], v[34:37], v[54:69]
	v_mfma_f32_32x32x16_bf16 v[54:69], v[94:97], v[46:49], v[54:69]
	s_nop 11
	v_cvt_pk_bf16_f32 v6, v54, v55
	v_cvt_pk_bf16_f32 v7, v56, v57
	v_cvt_pk_bf16_f32 v8, v58, v59
	v_cvt_pk_bf16_f32 v9, v60, v61
	v_cvt_pk_bf16_f32 v10, v62, v63
	v_cvt_pk_bf16_f32 v11, v64, v65
	v_cvt_pk_bf16_f32 v12, v66, v67
	v_cvt_pk_bf16_f32 v13, v68, v69
	v_permlane32_swap_b32_e32 v6, v8
	v_permlane32_swap_b32_e32 v7, v9
	v_permlane32_swap_b32_e32 v10, v12
	v_permlane32_swap_b32_e32 v11, v13
	global_store_dwordx4 v[124:125], v[6:9], off offset:1024
	global_store_dwordx4 v[124:125], v[10:13], off offset:1056
	s_waitcnt vmcnt(2)
	v_permlane32_swap_b32_e32 v146, v148
	v_permlane32_swap_b32_e32 v147, v149
	v_permlane32_swap_b32_e32 v150, v152
	v_permlane32_swap_b32_e32 v151, v153
	v_permlane32_swap_b32_e32 v154, v156
	v_permlane32_swap_b32_e32 v155, v157
	v_permlane32_swap_b32_e32 v158, v160
	v_permlane32_swap_b32_e32 v159, v161
	v_permlane32_swap_b32_e32 v162, v164
	v_permlane32_swap_b32_e32 v163, v165
	v_permlane32_swap_b32_e32 v166, v168
	v_permlane32_swap_b32_e32 v167, v169
	v_permlane32_swap_b32_e32 v170, v172
	v_permlane32_swap_b32_e32 v171, v173
	v_permlane32_swap_b32_e32 v174, v176
	v_permlane32_swap_b32_e32 v175, v177
	s_nop 1
	v_mfma_f32_32x32x16_bf16 v[6:21], v[146:149], v[38:41], 0
	v_mfma_f32_32x32x16_bf16 v[6:21], v[150:153], v[0:3], v[6:21]
	v_mfma_f32_32x32x16_bf16 v[6:21], v[154:157], v[42:45], v[6:21]
	v_mfma_f32_32x32x16_bf16 v[6:21], v[158:161], v[22:25], v[6:21]
	v_mfma_f32_32x32x16_bf16 v[6:21], v[162:165], v[26:29], v[6:21]
	v_mfma_f32_32x32x16_bf16 v[6:21], v[166:169], v[30:33], v[6:21]
	v_mfma_f32_32x32x16_bf16 v[6:21], v[170:173], v[34:37], v[6:21]
	v_mfma_f32_32x32x16_bf16 v[6:21], v[174:177], v[46:49], v[6:21]
	s_nop 11
	v_cvt_pk_bf16_f32 v0, v6, v7
	v_cvt_pk_bf16_f32 v1, v8, v9
	v_cvt_pk_bf16_f32 v2, v10, v11
	v_cvt_pk_bf16_f32 v3, v12, v13
	v_cvt_pk_bf16_f32 v6, v14, v15
	v_cvt_pk_bf16_f32 v7, v16, v17
	v_cvt_pk_bf16_f32 v8, v18, v19
	v_cvt_pk_bf16_f32 v9, v20, v21
	v_permlane32_swap_b32_e32 v0, v2
	v_permlane32_swap_b32_e32 v1, v3
	v_permlane32_swap_b32_e32 v6, v8
	v_permlane32_swap_b32_e32 v7, v9
	global_store_dwordx4 v[124:125], v[0:3], off offset:1088
	global_store_dwordx4 v[124:125], v[6:9], off offset:1120
